# phase 0 weight-tile loop: removed the vmcnt(0) that sat right after the next tile's loads on the common (no time-mix scale) path, so the next tile's loads overlap the current tile's barrier/transposed
# speedup vs baseline: 1.0081x; 1.0069x over previous
.LBB0_463:
	s_andn2_b64 vcc, exec, s[14:15]
	s_cbranch_vccnz .LBB0_466
	s_cmp_lg_u32 s6, 1
	v_mov_b32_e32 v12, 1.0
	s_cbranch_scc1 .LBB0_466
	s_load_dwordx2 s[14:15], s[0:1], 0x70
	v_add_u32_e32 v14, s7, v17
	v_ashrrev_i32_e32 v15, 31, v14
	s_waitcnt lgkmcnt(0)
	v_lshl_add_u64 v[14:15], v[14:15], 2, s[14:15]
	global_load_dword v12, v[14:15], off
	s_waitcnt vmcnt(0)
	v_sub_f32_e32 v12, 1.0, v12
